# EpiSwiglu: row-stat loads of the first three row groups issued in the last K iteration (behind the final MFMA blocks) so the epilogue starts without a load round trip
# baseline (speedup 1.0000x reference)
.Lfw_4:
	s_waitcnt lgkmcnt(0)
	s_barrier
	s_setprio 1
	s_waitcnt lgkmcnt(0)
	v_mfma_f32_16x16x32_bf16 v[60:63], v[130:133], v[198:201], v[60:63]
	v_mfma_f32_16x16x32_bf16 v[52:55], v[138:141], v[198:201], v[52:55]
	v_mfma_f32_16x16x32_bf16 v[44:47], v[130:133], v[222:225], v[44:47]
	v_mfma_f32_16x16x32_bf16 v[36:39], v[138:141], v[222:225], v[36:39]
	v_mfma_f32_16x16x32_bf16 v[28:31], v[130:133], v[230:233], v[28:31]
	v_mfma_f32_16x16x32_bf16 v[20:23], v[138:141], v[230:233], v[20:23]
	v_mfma_f32_16x16x32_bf16 v[12:15], v[130:133], v[238:241], v[12:15]
	v_mfma_f32_16x16x32_bf16 v[4:7], v[138:141], v[238:241], v[4:7]
	v_mfma_f32_16x16x32_bf16 v[60:63], v[134:137], v[202:205], v[60:63]
	v_mfma_f32_16x16x32_bf16 v[52:55], v[178:181], v[202:205], v[52:55]
	v_mfma_f32_16x16x32_bf16 v[44:47], v[134:137], v[226:229], v[44:47]
	v_mfma_f32_16x16x32_bf16 v[36:39], v[178:181], v[226:229], v[36:39]
	v_mfma_f32_16x16x32_bf16 v[28:31], v[134:137], v[234:237], v[28:31]
	v_mfma_f32_16x16x32_bf16 v[20:23], v[178:181], v[234:237], v[20:23]
	v_mfma_f32_16x16x32_bf16 v[12:15], v[134:137], v[242:245], v[12:15]
	v_mfma_f32_16x16x32_bf16 v[4:7], v[178:181], v[242:245], v[4:7]
	s_setprio 0
	s_setprio 1
	v_mfma_f32_16x16x32_bf16 v[56:59], v[182:185], v[198:201], v[56:59]
	v_mfma_f32_16x16x32_bf16 v[48:51], v[190:193], v[198:201], v[48:51]
	v_mfma_f32_16x16x32_bf16 v[40:43], v[182:185], v[222:225], v[40:43]
	v_mfma_f32_16x16x32_bf16 v[32:35], v[190:193], v[222:225], v[32:35]
	v_mfma_f32_16x16x32_bf16 v[24:27], v[182:185], v[230:233], v[24:27]
	v_mfma_f32_16x16x32_bf16 v[16:19], v[190:193], v[230:233], v[16:19]
	v_mfma_f32_16x16x32_bf16 v[8:11], v[182:185], v[238:241], v[8:11]
	v_mfma_f32_16x16x32_bf16 v[0:3], v[190:193], v[238:241], v[0:3]
	v_mfma_f32_16x16x32_bf16 v[56:59], v[186:189], v[202:205], v[56:59]
	v_mfma_f32_16x16x32_bf16 v[48:51], v[194:197], v[202:205], v[48:51]
	v_mfma_f32_16x16x32_bf16 v[40:43], v[186:189], v[226:229], v[40:43]
	v_mfma_f32_16x16x32_bf16 v[32:35], v[194:197], v[226:229], v[32:35]
	v_mfma_f32_16x16x32_bf16 v[24:27], v[186:189], v[234:237], v[24:27]
	v_mfma_f32_16x16x32_bf16 v[16:19], v[194:197], v[234:237], v[16:19]
	v_mfma_f32_16x16x32_bf16 v[8:11], v[186:189], v[242:245], v[8:11]
	v_mfma_f32_16x16x32_bf16 v[0:3], v[194:197], v[242:245], v[0:3]
	s_setprio 0
	s_barrier
	s_add_i32 s44, 0, 0x18000
	v_add_u32_e32 v173, s44, v169
	s_add_i32 s45, 0, 0x1c000
	ds_read_b128 v[130:133], v173
	ds_read_b128 v[134:137], v173 offset:1024
	ds_read_b128 v[138:141], v173 offset:2048
	ds_read_b128 v[178:181], v173 offset:3072
	v_add_u32_e32 v173, s45, v169
	ds_read_b128 v[182:185], v173
	ds_read_b128 v[186:189], v173 offset:1024
	ds_read_b128 v[190:193], v173 offset:2048
	ds_read_b128 v[194:197], v173 offset:3072
	s_add_u32 s22, s22, 0x40000
	s_addc_u32 s23, s23, 0
	s_mov_b32 m0, s31
	v_lshl_add_u64 v[214:215], s[22:23], 0, v[146:147]
	ds_read_b128 v[198:201], v149 offset:32768
	ds_read_b128 v[202:205], v149 offset:33792
	ds_read_b128 v[222:225], v149 offset:34816
	ds_read_b128 v[226:229], v149 offset:35840
	ds_read_b128 v[230:233], v149 offset:36864
	ds_read_b128 v[234:237], v149 offset:37888
	ds_read_b128 v[238:241], v149 offset:38912
	ds_read_b128 v[242:245], v149 offset:39936
	global_load_lds_dwordx4 v[214:215], off
	v_lshl_add_u64 v[214:215], s[22:23], 0, v[144:145]
	s_mov_b32 m0, s33
	s_nop 0
	global_load_lds_dwordx4 v[214:215], off
	s_waitcnt vmcnt(8)
	s_waitcnt lgkmcnt(0)
	s_barrier
	s_setprio 1
	s_waitcnt lgkmcnt(0)
	v_mfma_f32_16x16x32_bf16 v[118:121], v[130:133], v[198:201], v[118:121]
	v_mfma_f32_16x16x32_bf16 v[114:117], v[138:141], v[198:201], v[114:117]
	v_mfma_f32_16x16x32_bf16 v[110:113], v[130:133], v[222:225], v[110:113]
	v_mfma_f32_16x16x32_bf16 v[102:105], v[138:141], v[222:225], v[102:105]
	v_mfma_f32_16x16x32_bf16 v[92:95], v[130:133], v[230:233], v[92:95]
	v_mfma_f32_16x16x32_bf16 v[84:87], v[138:141], v[230:233], v[84:87]
	v_mfma_f32_16x16x32_bf16 v[76:79], v[130:133], v[238:241], v[76:79]
	v_mfma_f32_16x16x32_bf16 v[68:71], v[138:141], v[238:241], v[68:71]
	v_mfma_f32_16x16x32_bf16 v[118:121], v[134:137], v[202:205], v[118:121]
	v_mfma_f32_16x16x32_bf16 v[114:117], v[178:181], v[202:205], v[114:117]
	v_mfma_f32_16x16x32_bf16 v[110:113], v[134:137], v[226:229], v[110:113]
	v_mfma_f32_16x16x32_bf16 v[102:105], v[178:181], v[226:229], v[102:105]
	v_mfma_f32_16x16x32_bf16 v[92:95], v[134:137], v[234:237], v[92:95]
	v_mfma_f32_16x16x32_bf16 v[84:87], v[178:181], v[234:237], v[84:87]
	v_mfma_f32_16x16x32_bf16 v[76:79], v[134:137], v[242:245], v[76:79]
	v_mfma_f32_16x16x32_bf16 v[68:71], v[178:181], v[242:245], v[68:71]
	s_setprio 0
	s_setprio 1
	v_mfma_f32_16x16x32_bf16 v[126:129], v[182:185], v[198:201], v[126:129]
	v_mfma_f32_16x16x32_bf16 v[122:125], v[190:193], v[198:201], v[122:125]
	v_mfma_f32_16x16x32_bf16 v[106:109], v[182:185], v[222:225], v[106:109]
	v_mfma_f32_16x16x32_bf16 v[98:101], v[190:193], v[222:225], v[98:101]
	v_mfma_f32_16x16x32_bf16 v[88:91], v[182:185], v[230:233], v[88:91]
	v_mfma_f32_16x16x32_bf16 v[80:83], v[190:193], v[230:233], v[80:83]
	v_mfma_f32_16x16x32_bf16 v[72:75], v[182:185], v[238:241], v[72:75]
	v_mfma_f32_16x16x32_bf16 v[64:67], v[190:193], v[238:241], v[64:67]
	v_mfma_f32_16x16x32_bf16 v[126:129], v[186:189], v[202:205], v[126:129]
	v_mfma_f32_16x16x32_bf16 v[122:125], v[194:197], v[202:205], v[122:125]
	v_mfma_f32_16x16x32_bf16 v[106:109], v[186:189], v[226:229], v[106:109]
	v_mfma_f32_16x16x32_bf16 v[98:101], v[194:197], v[226:229], v[98:101]
	v_mfma_f32_16x16x32_bf16 v[88:91], v[186:189], v[234:237], v[88:91]
	v_mfma_f32_16x16x32_bf16 v[80:83], v[194:197], v[234:237], v[80:83]
	v_mfma_f32_16x16x32_bf16 v[72:75], v[186:189], v[242:245], v[72:75]
	v_mfma_f32_16x16x32_bf16 v[64:67], v[194:197], v[242:245], v[64:67]
	s_setprio 0
	s_barrier
	s_add_i32 s22, s44, s27
	v_lshl_add_u64 v[214:215], v[246:247], 0, s[90:91]
	s_mov_b32 m0, s22
	ds_read_b128 v[198:201], v149 offset:49152
	ds_read_b128 v[202:205], v149 offset:50176
	ds_read_b128 v[222:225], v149 offset:51200
	ds_read_b128 v[226:229], v149 offset:52224
	ds_read_b128 v[230:233], v149 offset:53248
	ds_read_b128 v[234:237], v149 offset:54272
	ds_read_b128 v[238:241], v149 offset:55296
	ds_read_b128 v[242:245], v149 offset:56320
	global_load_lds_dwordx4 v[214:215], off
	s_add_i32 m0, s22, 0x2000
	s_add_u32 s20, s20, 0x40080
	v_lshl_add_u64 v[214:215], v[248:249], 0, s[90:91]
	s_addc_u32 s21, s21, 0
	s_add_i32 s22, s45, s27
	global_load_lds_dwordx4 v[214:215], off
	v_lshl_add_u64 v[214:215], s[20:21], 0, v[96:97]
	s_mov_b32 m0, s22
	v_lshl_add_u64 v[212:213], v[212:213], 0, s[90:91]
	global_load_lds_dwordx4 v[214:215], off
	v_lshl_add_u64 v[214:215], s[20:21], 0, v[142:143]
	s_add_i32 m0, s22, 0x2000
	s_nop 0
	global_load_lds_dwordx4 v[214:215], off
	v_lshl_add_u64 v[214:215], v[220:221], 0, s[90:91]
	s_mov_b32 m0, s34
	s_nop 0
	global_load_lds_dwordx4 v[214:215], off
	s_mov_b32 m0, s35
	s_nop 0
	global_load_lds_dwordx4 v[212:213], off
	s_waitcnt vmcnt(8)
	s_cmp_lg_u32 s43, 12
	s_cbranch_scc1 .Lrp_skip
	v_lshl_add_u32 v164, s0, 8, v148
	v_ashrrev_i32_e32 v165, 31, v164
	v_lshl_add_u64 v[164:165], v[164:165], 4, s[8:9]
	global_load_dwordx4 v[152:155], v[164:165], off
	global_load_dwordx4 v[156:159], v[164:165], off offset:256
	global_load_dwordx4 v[160:163], v[164:165], off offset:512
.Lrp_skip:
	s_waitcnt lgkmcnt(0)
	s_barrier
	s_setprio 1
	s_waitcnt lgkmcnt(0)
	v_mfma_f32_16x16x32_bf16 v[60:63], v[130:133], v[198:201], v[60:63]
	v_mfma_f32_16x16x32_bf16 v[52:55], v[138:141], v[198:201], v[52:55]
	v_mfma_f32_16x16x32_bf16 v[44:47], v[130:133], v[222:225], v[44:47]
	v_mfma_f32_16x16x32_bf16 v[36:39], v[138:141], v[222:225], v[36:39]
	v_mfma_f32_16x16x32_bf16 v[28:31], v[130:133], v[230:233], v[28:31]
	v_mfma_f32_16x16x32_bf16 v[20:23], v[138:141], v[230:233], v[20:23]
	v_mfma_f32_16x16x32_bf16 v[12:15], v[130:133], v[238:241], v[12:15]
	v_mfma_f32_16x16x32_bf16 v[4:7], v[138:141], v[238:241], v[4:7]
	v_mfma_f32_16x16x32_bf16 v[60:63], v[134:137], v[202:205], v[60:63]
	v_mfma_f32_16x16x32_bf16 v[52:55], v[178:181], v[202:205], v[52:55]
	v_mfma_f32_16x16x32_bf16 v[44:47], v[134:137], v[226:229], v[44:47]
	v_mfma_f32_16x16x32_bf16 v[36:39], v[178:181], v[226:229], v[36:39]
	v_mfma_f32_16x16x32_bf16 v[28:31], v[134:137], v[234:237], v[28:31]
	v_mfma_f32_16x16x32_bf16 v[20:23], v[178:181], v[234:237], v[20:23]
	v_mfma_f32_16x16x32_bf16 v[12:15], v[134:137], v[242:245], v[12:15]
	v_mfma_f32_16x16x32_bf16 v[4:7], v[178:181], v[242:245], v[4:7]
	s_setprio 0
	s_setprio 1
	v_mfma_f32_16x16x32_bf16 v[56:59], v[182:185], v[198:201], v[56:59]
	v_mfma_f32_16x16x32_bf16 v[48:51], v[190:193], v[198:201], v[48:51]
	v_mfma_f32_16x16x32_bf16 v[40:43], v[182:185], v[222:225], v[40:43]
	v_mfma_f32_16x16x32_bf16 v[32:35], v[190:193], v[222:225], v[32:35]
	v_mfma_f32_16x16x32_bf16 v[24:27], v[182:185], v[230:233], v[24:27]
	v_mfma_f32_16x16x32_bf16 v[16:19], v[190:193], v[230:233], v[16:19]
	v_mfma_f32_16x16x32_bf16 v[8:11], v[182:185], v[238:241], v[8:11]
	v_mfma_f32_16x16x32_bf16 v[0:3], v[190:193], v[238:241], v[0:3]
	v_mfma_f32_16x16x32_bf16 v[56:59], v[186:189], v[202:205], v[56:59]
	v_mfma_f32_16x16x32_bf16 v[48:51], v[194:197], v[202:205], v[48:51]
	v_mfma_f32_16x16x32_bf16 v[40:43], v[186:189], v[226:229], v[40:43]
	v_mfma_f32_16x16x32_bf16 v[32:35], v[194:197], v[226:229], v[32:35]
	v_mfma_f32_16x16x32_bf16 v[24:27], v[186:189], v[234:237], v[24:27]
	v_mfma_f32_16x16x32_bf16 v[16:19], v[194:197], v[234:237], v[16:19]
	v_mfma_f32_16x16x32_bf16 v[8:11], v[186:189], v[242:245], v[8:11]
	v_mfma_f32_16x16x32_bf16 v[0:3], v[194:197], v[242:245], v[0:3]
	s_setprio 0
	s_barrier
	s_mov_b32 s101, 0
	s_add_i32 s43, s43, 2
	s_add_u32 s2, s2, 0x100
	s_addc_u32 s3, s3, 0
	s_add_u32 s41, s41, 0x100
	s_addc_u32 s42, s42, 0
	s_cmp_gt_u32 s43, 13
	s_cbranch_scc0 .LBB0_1131
	s_and_b64 vcc, exec, s[10:11]
	s_cbranch_vccz .LBB0_1134
	s_barrier
.LBB0_1134:
	v_lshl_add_u32 v130, s0, 8, v148
	v_ashrrev_i32_e32 v131, 31, v130
	v_lshl_add_u64 v[190:191], v[130:131], 4, s[8:9]
	global_load_dwordx4 v[234:237], v[190:191], off offset:768
	global_load_dwordx4 v[238:241], v[190:191], off offset:2048
	global_load_dwordx4 v[242:245], v[190:191], off offset:2304
	global_load_dwordx4 v[198:201], v[190:191], off offset:2560
	global_load_dwordx4 v[202:205], v[190:191], off offset:2816
	s_lshl_b32 s1, s1, 1
	s_or_b32 s1, s1, s36
	s_mul_hi_i32 s2, s0, 44
	s_mul_i32 s0, s0, 44
	s_ashr_i32 s3, s1, 31
	s_add_u32 s0, s0, s1
	s_addc_u32 s1, s2, s3
	s_lshl_b64 s[0:1], s[0:1], 15
	v_lshl_add_u64 v[178:179], v[166:167], 0, s[0:1]
	v_lshl_add_u64 v[178:179], v[178:179], 0, v[150:151]
	s_mov_b64 s[2:3], 0x1000
	v_lshl_add_u64 v[180:181], v[178:179], 0, s[2:3]
	s_mov_b64 s[2:3], 0x5000
	v_lshl_add_u64 v[182:183], v[178:179], 0, s[2:3]
	s_mov_b32 s2, 0xbfb8aa3b
	s_mov_b32 s3, 0xbfb8aa3b
	s_mov_b32 s100, 1.0
	s_mov_b32 s101, 1.0
	s_waitcnt vmcnt(7)
	v_add_f32_e32 v140, v152, v153
	v_add_f32_e32 v141, v154, v155
	v_add_f32_e32 v140, v140, v141
	v_fmamk_f32 v140, v140, 0x3a800000, v207
	v_rsq_f32_e32 v184, v140
	s_nop 0
	v_pk_mul_f32 v[118:119], v[118:119], v[184:185] op_sel_hi:[1,0]
	v_pk_mul_f32 v[120:121], v[120:121], v[184:185] op_sel_hi:[1,0]
	v_pk_mul_f32 v[114:115], v[114:115], v[184:185] op_sel_hi:[1,0]
	v_pk_mul_f32 v[116:117], v[116:117], v[184:185] op_sel_hi:[1,0]
	v_pk_mul_f32 v[126:127], v[126:127], v[184:185] op_sel_hi:[1,0]
	v_pk_mul_f32 v[128:129], v[128:129], v[184:185] op_sel_hi:[1,0]
	v_pk_mul_f32 v[122:123], v[122:123], v[184:185] op_sel_hi:[1,0]
	v_pk_mul_f32 v[124:125], v[124:125], v[184:185] op_sel_hi:[1,0]
	v_pk_mul_f32 v[132:133], v[118:119], s[2:3]
	v_pk_mul_f32 v[134:135], v[120:121], s[2:3]
	v_pk_mul_f32 v[136:137], v[114:115], s[2:3]
	v_pk_mul_f32 v[138:139], v[116:117], s[2:3]
	v_exp_f32_e32 v132, v132
	v_exp_f32_e32 v133, v133
	v_exp_f32_e32 v134, v134
	v_exp_f32_e32 v135, v135
	v_exp_f32_e32 v136, v136
	v_exp_f32_e32 v137, v137
	v_exp_f32_e32 v138, v138
	v_exp_f32_e32 v139, v139
	v_pk_add_f32 v[132:133], v[132:133], s[100:101]
	v_pk_add_f32 v[134:135], v[134:135], s[100:101]
	v_pk_add_f32 v[136:137], v[136:137], s[100:101]
	v_pk_add_f32 v[138:139], v[138:139], s[100:101]
	v_rcp_f32_e32 v132, v132
	v_rcp_f32_e32 v133, v133
	v_rcp_f32_e32 v134, v134
	v_rcp_f32_e32 v135, v135
	v_rcp_f32_e32 v136, v136
	v_rcp_f32_e32 v137, v137
	v_rcp_f32_e32 v138, v138
	v_rcp_f32_e32 v139, v139
	v_pk_mul_f32 v[118:119], v[118:119], v[132:133]
	v_pk_mul_f32 v[120:121], v[120:121], v[134:135]
	v_pk_mul_f32 v[114:115], v[114:115], v[136:137]
	v_pk_mul_f32 v[116:117], v[116:117], v[138:139]
	v_pk_mul_f32 v[118:119], v[118:119], v[126:127]
	v_pk_mul_f32 v[120:121], v[120:121], v[128:129]
	v_pk_mul_f32 v[114:115], v[114:115], v[122:123]
	v_pk_mul_f32 v[116:117], v[116:117], v[124:125]
	v_cvt_pk_bf16_f32 v192, v118, v119
	v_cvt_pk_bf16_f32 v193, v120, v121
	v_cvt_pk_bf16_f32 v194, v114, v115
	v_cvt_pk_bf16_f32 v195, v116, v117
	global_store_dwordx4 v[180:181], v[192:195], off offset:-4096
	s_waitcnt vmcnt(7)
	v_add_f32_e32 v140, v156, v157
	v_add_f32_e32 v141, v158, v159
	v_add_f32_e32 v140, v140, v141
	v_fmamk_f32 v140, v140, 0x3a800000, v207
	v_rsq_f32_e32 v184, v140
	s_nop 0
	v_pk_mul_f32 v[110:111], v[110:111], v[184:185] op_sel_hi:[1,0]
	v_pk_mul_f32 v[112:113], v[112:113], v[184:185] op_sel_hi:[1,0]
	v_pk_mul_f32 v[102:103], v[102:103], v[184:185] op_sel_hi:[1,0]
	v_pk_mul_f32 v[104:105], v[104:105], v[184:185] op_sel_hi:[1,0]
	v_pk_mul_f32 v[106:107], v[106:107], v[184:185] op_sel_hi:[1,0]
	v_pk_mul_f32 v[108:109], v[108:109], v[184:185] op_sel_hi:[1,0]
	v_pk_mul_f32 v[98:99], v[98:99], v[184:185] op_sel_hi:[1,0]
	v_pk_mul_f32 v[100:101], v[100:101], v[184:185] op_sel_hi:[1,0]
	v_pk_mul_f32 v[132:133], v[110:111], s[2:3]
	v_pk_mul_f32 v[134:135], v[112:113], s[2:3]
	v_pk_mul_f32 v[136:137], v[102:103], s[2:3]
	v_pk_mul_f32 v[138:139], v[104:105], s[2:3]
	v_exp_f32_e32 v132, v132
	v_exp_f32_e32 v133, v133
	v_exp_f32_e32 v134, v134
	v_exp_f32_e32 v135, v135
	v_exp_f32_e32 v136, v136
	v_exp_f32_e32 v137, v137
	v_exp_f32_e32 v138, v138
	v_exp_f32_e32 v139, v139
	v_pk_add_f32 v[132:133], v[132:133], s[100:101]
	v_pk_add_f32 v[134:135], v[134:135], s[100:101]
	v_pk_add_f32 v[136:137], v[136:137], s[100:101]
	v_pk_add_f32 v[138:139], v[138:139], s[100:101]
	v_rcp_f32_e32 v132, v132
	v_rcp_f32_e32 v133, v133
	v_rcp_f32_e32 v134, v134
	v_rcp_f32_e32 v135, v135
	v_rcp_f32_e32 v136, v136
	v_rcp_f32_e32 v137, v137
	v_rcp_f32_e32 v138, v138
	v_rcp_f32_e32 v139, v139
	v_pk_mul_f32 v[110:111], v[110:111], v[132:133]
	v_pk_mul_f32 v[112:113], v[112:113], v[134:135]
	v_pk_mul_f32 v[102:103], v[102:103], v[136:137]
	v_pk_mul_f32 v[104:105], v[104:105], v[138:139]
	v_pk_mul_f32 v[110:111], v[110:111], v[106:107]
	v_pk_mul_f32 v[112:113], v[112:113], v[108:109]
	v_pk_mul_f32 v[102:103], v[102:103], v[98:99]
	v_pk_mul_f32 v[104:105], v[104:105], v[100:101]
	v_cvt_pk_bf16_f32 v186, v110, v111
	v_cvt_pk_bf16_f32 v187, v112, v113
	v_cvt_pk_bf16_f32 v188, v102, v103
	v_cvt_pk_bf16_f32 v189, v104, v105
	global_store_dwordx4 v[180:181], v[186:189], off offset:-2048
	s_waitcnt vmcnt(7)
	v_add_f32_e32 v140, v160, v161
	v_add_f32_e32 v141, v162, v163
	v_add_f32_e32 v140, v140, v141
	v_fmamk_f32 v140, v140, 0x3a800000, v207
	v_rsq_f32_e32 v184, v140
	s_nop 0
	v_pk_mul_f32 v[92:93], v[92:93], v[184:185] op_sel_hi:[1,0]
	v_pk_mul_f32 v[94:95], v[94:95], v[184:185] op_sel_hi:[1,0]
	v_pk_mul_f32 v[84:85], v[84:85], v[184:185] op_sel_hi:[1,0]
	v_pk_mul_f32 v[86:87], v[86:87], v[184:185] op_sel_hi:[1,0]
	v_pk_mul_f32 v[88:89], v[88:89], v[184:185] op_sel_hi:[1,0]
	v_pk_mul_f32 v[90:91], v[90:91], v[184:185] op_sel_hi:[1,0]
	v_pk_mul_f32 v[80:81], v[80:81], v[184:185] op_sel_hi:[1,0]
	v_pk_mul_f32 v[82:83], v[82:83], v[184:185] op_sel_hi:[1,0]
	v_pk_mul_f32 v[132:133], v[92:93], s[2:3]
	v_pk_mul_f32 v[134:135], v[94:95], s[2:3]
	v_pk_mul_f32 v[136:137], v[84:85], s[2:3]
	v_pk_mul_f32 v[138:139], v[86:87], s[2:3]
	v_exp_f32_e32 v132, v132
	v_exp_f32_e32 v133, v133
	v_exp_f32_e32 v134, v134
	v_exp_f32_e32 v135, v135
	v_exp_f32_e32 v136, v136
	v_exp_f32_e32 v137, v137
	v_exp_f32_e32 v138, v138
	v_exp_f32_e32 v139, v139
	v_pk_add_f32 v[132:133], v[132:133], s[100:101]
	v_pk_add_f32 v[134:135], v[134:135], s[100:101]
	v_pk_add_f32 v[136:137], v[136:137], s[100:101]
	v_pk_add_f32 v[138:139], v[138:139], s[100:101]
	v_rcp_f32_e32 v132, v132
	v_rcp_f32_e32 v133, v133
	v_rcp_f32_e32 v134, v134
	v_rcp_f32_e32 v135, v135
	v_rcp_f32_e32 v136, v136
	v_rcp_f32_e32 v137, v137
	v_rcp_f32_e32 v138, v138
	v_rcp_f32_e32 v139, v139
	v_pk_mul_f32 v[92:93], v[92:93], v[132:133]
	v_pk_mul_f32 v[94:95], v[94:95], v[134:135]
	v_pk_mul_f32 v[84:85], v[84:85], v[136:137]
	v_pk_mul_f32 v[86:87], v[86:87], v[138:139]
	v_pk_mul_f32 v[92:93], v[92:93], v[88:89]
	v_pk_mul_f32 v[94:95], v[94:95], v[90:91]
	v_pk_mul_f32 v[84:85], v[84:85], v[80:81]
	v_pk_mul_f32 v[86:87], v[86:87], v[82:83]
	v_cvt_pk_bf16_f32 v192, v92, v93
	v_cvt_pk_bf16_f32 v193, v94, v95
	v_cvt_pk_bf16_f32 v194, v84, v85
	v_cvt_pk_bf16_f32 v195, v86, v87
	global_store_dwordx4 v[180:181], v[192:195], off
	s_waitcnt vmcnt(7)
	v_add_f32_e32 v140, v234, v235
	v_add_f32_e32 v141, v236, v237
	v_add_f32_e32 v140, v140, v141
	v_fmamk_f32 v140, v140, 0x3a800000, v207
	v_rsq_f32_e32 v184, v140
	s_nop 0
	v_pk_mul_f32 v[76:77], v[76:77], v[184:185] op_sel_hi:[1,0]
	v_pk_mul_f32 v[78:79], v[78:79], v[184:185] op_sel_hi:[1,0]
	v_pk_mul_f32 v[68:69], v[68:69], v[184:185] op_sel_hi:[1,0]
	v_pk_mul_f32 v[70:71], v[70:71], v[184:185] op_sel_hi:[1,0]
	v_pk_mul_f32 v[72:73], v[72:73], v[184:185] op_sel_hi:[1,0]
	v_pk_mul_f32 v[74:75], v[74:75], v[184:185] op_sel_hi:[1,0]
	v_pk_mul_f32 v[64:65], v[64:65], v[184:185] op_sel_hi:[1,0]
	v_pk_mul_f32 v[66:67], v[66:67], v[184:185] op_sel_hi:[1,0]
	v_pk_mul_f32 v[132:133], v[76:77], s[2:3]
	v_pk_mul_f32 v[134:135], v[78:79], s[2:3]
	v_pk_mul_f32 v[136:137], v[68:69], s[2:3]
	v_pk_mul_f32 v[138:139], v[70:71], s[2:3]
	v_exp_f32_e32 v132, v132
	v_exp_f32_e32 v133, v133
	v_exp_f32_e32 v134, v134
	v_exp_f32_e32 v135, v135
	v_exp_f32_e32 v136, v136
	v_exp_f32_e32 v137, v137
	v_exp_f32_e32 v138, v138
	v_exp_f32_e32 v139, v139
	v_pk_add_f32 v[132:133], v[132:133], s[100:101]
	v_pk_add_f32 v[134:135], v[134:135], s[100:101]
	v_pk_add_f32 v[136:137], v[136:137], s[100:101]
	v_pk_add_f32 v[138:139], v[138:139], s[100:101]
	v_rcp_f32_e32 v132, v132
	v_rcp_f32_e32 v133, v133
	v_rcp_f32_e32 v134, v134
	v_rcp_f32_e32 v135, v135
	v_rcp_f32_e32 v136, v136
	v_rcp_f32_e32 v137, v137
	v_rcp_f32_e32 v138, v138
	v_rcp_f32_e32 v139, v139
	v_pk_mul_f32 v[76:77], v[76:77], v[132:133]
	v_pk_mul_f32 v[78:79], v[78:79], v[134:135]
	v_pk_mul_f32 v[68:69], v[68:69], v[136:137]
	v_pk_mul_f32 v[70:71], v[70:71], v[138:139]
	v_pk_mul_f32 v[76:77], v[76:77], v[72:73]
	v_pk_mul_f32 v[78:79], v[78:79], v[74:75]
	v_pk_mul_f32 v[68:69], v[68:69], v[64:65]
	v_pk_mul_f32 v[70:71], v[70:71], v[66:67]
	v_cvt_pk_bf16_f32 v186, v76, v77
	v_cvt_pk_bf16_f32 v187, v78, v79
	v_cvt_pk_bf16_f32 v188, v68, v69
	v_cvt_pk_bf16_f32 v189, v70, v71
	global_store_dwordx4 v[180:181], v[186:189], off offset:2048
	s_waitcnt vmcnt(7)
	v_add_f32_e32 v140, v238, v239
	v_add_f32_e32 v141, v240, v241
	v_add_f32_e32 v140, v140, v141
	v_fmamk_f32 v140, v140, 0x3a800000, v207
	v_rsq_f32_e32 v184, v140
	s_nop 0
	v_pk_mul_f32 v[60:61], v[60:61], v[184:185] op_sel_hi:[1,0]
	v_pk_mul_f32 v[62:63], v[62:63], v[184:185] op_sel_hi:[1,0]
	v_pk_mul_f32 v[52:53], v[52:53], v[184:185] op_sel_hi:[1,0]
	v_pk_mul_f32 v[54:55], v[54:55], v[184:185] op_sel_hi:[1,0]
	v_pk_mul_f32 v[56:57], v[56:57], v[184:185] op_sel_hi:[1,0]
	v_pk_mul_f32 v[58:59], v[58:59], v[184:185] op_sel_hi:[1,0]
	v_pk_mul_f32 v[48:49], v[48:49], v[184:185] op_sel_hi:[1,0]
	v_pk_mul_f32 v[50:51], v[50:51], v[184:185] op_sel_hi:[1,0]
	v_pk_mul_f32 v[132:133], v[60:61], s[2:3]
	v_pk_mul_f32 v[134:135], v[62:63], s[2:3]
	v_pk_mul_f32 v[136:137], v[52:53], s[2:3]
	v_pk_mul_f32 v[138:139], v[54:55], s[2:3]
	v_exp_f32_e32 v132, v132
	v_exp_f32_e32 v133, v133
	v_exp_f32_e32 v134, v134
	v_exp_f32_e32 v135, v135
	v_exp_f32_e32 v136, v136
	v_exp_f32_e32 v137, v137
	v_exp_f32_e32 v138, v138
	v_exp_f32_e32 v139, v139
	v_pk_add_f32 v[132:133], v[132:133], s[100:101]
	v_pk_add_f32 v[134:135], v[134:135], s[100:101]
	v_pk_add_f32 v[136:137], v[136:137], s[100:101]
	v_pk_add_f32 v[138:139], v[138:139], s[100:101]
	v_rcp_f32_e32 v132, v132
	v_rcp_f32_e32 v133, v133
	v_rcp_f32_e32 v134, v134
	v_rcp_f32_e32 v135, v135
	v_rcp_f32_e32 v136, v136
	v_rcp_f32_e32 v137, v137
	v_rcp_f32_e32 v138, v138
	v_rcp_f32_e32 v139, v139
	v_pk_mul_f32 v[60:61], v[60:61], v[132:133]
	v_pk_mul_f32 v[62:63], v[62:63], v[134:135]
	v_pk_mul_f32 v[52:53], v[52:53], v[136:137]
	v_pk_mul_f32 v[54:55], v[54:55], v[138:139]
	v_pk_mul_f32 v[60:61], v[60:61], v[56:57]
	v_pk_mul_f32 v[62:63], v[62:63], v[58:59]
	v_pk_mul_f32 v[52:53], v[52:53], v[48:49]
	v_pk_mul_f32 v[54:55], v[54:55], v[50:51]
	v_cvt_pk_bf16_f32 v192, v60, v61
	v_cvt_pk_bf16_f32 v193, v62, v63
	v_cvt_pk_bf16_f32 v194, v52, v53
	v_cvt_pk_bf16_f32 v195, v54, v55
	global_store_dwordx4 v[182:183], v[192:195], off offset:-4096
	s_waitcnt vmcnt(7)
	v_add_f32_e32 v140, v242, v243
	v_add_f32_e32 v141, v244, v245
	v_add_f32_e32 v140, v140, v141
	v_fmamk_f32 v140, v140, 0x3a800000, v207
	v_rsq_f32_e32 v184, v140
	s_nop 0
	v_pk_mul_f32 v[44:45], v[44:45], v[184:185] op_sel_hi:[1,0]
	v_pk_mul_f32 v[46:47], v[46:47], v[184:185] op_sel_hi:[1,0]
	v_pk_mul_f32 v[36:37], v[36:37], v[184:185] op_sel_hi:[1,0]
	v_pk_mul_f32 v[38:39], v[38:39], v[184:185] op_sel_hi:[1,0]
	v_pk_mul_f32 v[40:41], v[40:41], v[184:185] op_sel_hi:[1,0]
	v_pk_mul_f32 v[42:43], v[42:43], v[184:185] op_sel_hi:[1,0]
	v_pk_mul_f32 v[32:33], v[32:33], v[184:185] op_sel_hi:[1,0]
	v_pk_mul_f32 v[34:35], v[34:35], v[184:185] op_sel_hi:[1,0]
	v_pk_mul_f32 v[132:133], v[44:45], s[2:3]
	v_pk_mul_f32 v[134:135], v[46:47], s[2:3]
	v_pk_mul_f32 v[136:137], v[36:37], s[2:3]
	v_pk_mul_f32 v[138:139], v[38:39], s[2:3]
	v_exp_f32_e32 v132, v132
	v_exp_f32_e32 v133, v133
	v_exp_f32_e32 v134, v134
	v_exp_f32_e32 v135, v135
	v_exp_f32_e32 v136, v136
	v_exp_f32_e32 v137, v137
	v_exp_f32_e32 v138, v138
	v_exp_f32_e32 v139, v139
	v_pk_add_f32 v[132:133], v[132:133], s[100:101]
	v_pk_add_f32 v[134:135], v[134:135], s[100:101]
	v_pk_add_f32 v[136:137], v[136:137], s[100:101]
	v_pk_add_f32 v[138:139], v[138:139], s[100:101]
	v_rcp_f32_e32 v132, v132
	v_rcp_f32_e32 v133, v133
	v_rcp_f32_e32 v134, v134
	v_rcp_f32_e32 v135, v135
	v_rcp_f32_e32 v136, v136
	v_rcp_f32_e32 v137, v137
	v_rcp_f32_e32 v138, v138
	v_rcp_f32_e32 v139, v139
	v_pk_mul_f32 v[44:45], v[44:45], v[132:133]
	v_pk_mul_f32 v[46:47], v[46:47], v[134:135]
	v_pk_mul_f32 v[36:37], v[36:37], v[136:137]
	v_pk_mul_f32 v[38:39], v[38:39], v[138:139]
	v_pk_mul_f32 v[44:45], v[44:45], v[40:41]
	v_pk_mul_f32 v[46:47], v[46:47], v[42:43]
	v_pk_mul_f32 v[36:37], v[36:37], v[32:33]
	v_pk_mul_f32 v[38:39], v[38:39], v[34:35]
	v_cvt_pk_bf16_f32 v186, v44, v45
	v_cvt_pk_bf16_f32 v187, v46, v47
	v_cvt_pk_bf16_f32 v188, v36, v37
	v_cvt_pk_bf16_f32 v189, v38, v39
	global_store_dwordx4 v[182:183], v[186:189], off offset:-2048
	s_waitcnt vmcnt(7)
	v_add_f32_e32 v140, v198, v199
	v_add_f32_e32 v141, v200, v201
	v_add_f32_e32 v140, v140, v141
	v_fmamk_f32 v140, v140, 0x3a800000, v207
	v_rsq_f32_e32 v184, v140
	s_nop 0
	v_pk_mul_f32 v[28:29], v[28:29], v[184:185] op_sel_hi:[1,0]
	v_pk_mul_f32 v[30:31], v[30:31], v[184:185] op_sel_hi:[1,0]
	v_pk_mul_f32 v[20:21], v[20:21], v[184:185] op_sel_hi:[1,0]
	v_pk_mul_f32 v[22:23], v[22:23], v[184:185] op_sel_hi:[1,0]
	v_pk_mul_f32 v[24:25], v[24:25], v[184:185] op_sel_hi:[1,0]
	v_pk_mul_f32 v[26:27], v[26:27], v[184:185] op_sel_hi:[1,0]
	v_pk_mul_f32 v[16:17], v[16:17], v[184:185] op_sel_hi:[1,0]
	v_pk_mul_f32 v[18:19], v[18:19], v[184:185] op_sel_hi:[1,0]
	v_pk_mul_f32 v[132:133], v[28:29], s[2:3]
	v_pk_mul_f32 v[134:135], v[30:31], s[2:3]
	v_pk_mul_f32 v[136:137], v[20:21], s[2:3]
	v_pk_mul_f32 v[138:139], v[22:23], s[2:3]
	v_exp_f32_e32 v132, v132
	v_exp_f32_e32 v133, v133
	v_exp_f32_e32 v134, v134
	v_exp_f32_e32 v135, v135
	v_exp_f32_e32 v136, v136
	v_exp_f32_e32 v137, v137
	v_exp_f32_e32 v138, v138
	v_exp_f32_e32 v139, v139
	v_pk_add_f32 v[132:133], v[132:133], s[100:101]
	v_pk_add_f32 v[134:135], v[134:135], s[100:101]
	v_pk_add_f32 v[136:137], v[136:137], s[100:101]
	v_pk_add_f32 v[138:139], v[138:139], s[100:101]
	v_rcp_f32_e32 v132, v132
	v_rcp_f32_e32 v133, v133
	v_rcp_f32_e32 v134, v134
	v_rcp_f32_e32 v135, v135
	v_rcp_f32_e32 v136, v136
	v_rcp_f32_e32 v137, v137
	v_rcp_f32_e32 v138, v138
	v_rcp_f32_e32 v139, v139
	v_pk_mul_f32 v[28:29], v[28:29], v[132:133]
	v_pk_mul_f32 v[30:31], v[30:31], v[134:135]
	v_pk_mul_f32 v[20:21], v[20:21], v[136:137]
	v_pk_mul_f32 v[22:23], v[22:23], v[138:139]
	v_pk_mul_f32 v[28:29], v[28:29], v[24:25]
	v_pk_mul_f32 v[30:31], v[30:31], v[26:27]
	v_pk_mul_f32 v[20:21], v[20:21], v[16:17]
	v_pk_mul_f32 v[22:23], v[22:23], v[18:19]
	v_cvt_pk_bf16_f32 v192, v28, v29
	v_cvt_pk_bf16_f32 v193, v30, v31
	v_cvt_pk_bf16_f32 v194, v20, v21
	v_cvt_pk_bf16_f32 v195, v22, v23
	global_store_dwordx4 v[182:183], v[192:195], off
	s_waitcnt vmcnt(7)
	v_add_f32_e32 v140, v202, v203
	v_add_f32_e32 v141, v204, v205
	v_add_f32_e32 v140, v140, v141
	v_fmamk_f32 v140, v140, 0x3a800000, v207
	v_rsq_f32_e32 v184, v140
	s_nop 0
	v_pk_mul_f32 v[12:13], v[12:13], v[184:185] op_sel_hi:[1,0]
	v_pk_mul_f32 v[14:15], v[14:15], v[184:185] op_sel_hi:[1,0]
	v_pk_mul_f32 v[4:5], v[4:5], v[184:185] op_sel_hi:[1,0]
	v_pk_mul_f32 v[6:7], v[6:7], v[184:185] op_sel_hi:[1,0]
	v_pk_mul_f32 v[8:9], v[8:9], v[184:185] op_sel_hi:[1,0]
	v_pk_mul_f32 v[10:11], v[10:11], v[184:185] op_sel_hi:[1,0]
	v_pk_mul_f32 v[0:1], v[0:1], v[184:185] op_sel_hi:[1,0]
	v_pk_mul_f32 v[2:3], v[2:3], v[184:185] op_sel_hi:[1,0]
	v_pk_mul_f32 v[132:133], v[12:13], s[2:3]
	v_pk_mul_f32 v[134:135], v[14:15], s[2:3]
	v_pk_mul_f32 v[136:137], v[4:5], s[2:3]
	v_pk_mul_f32 v[138:139], v[6:7], s[2:3]
	v_exp_f32_e32 v132, v132
	v_exp_f32_e32 v133, v133
	v_exp_f32_e32 v134, v134
	v_exp_f32_e32 v135, v135
	v_exp_f32_e32 v136, v136
	v_exp_f32_e32 v137, v137
	v_exp_f32_e32 v138, v138
	v_exp_f32_e32 v139, v139
	v_pk_add_f32 v[132:133], v[132:133], s[100:101]
	v_pk_add_f32 v[134:135], v[134:135], s[100:101]
	v_pk_add_f32 v[136:137], v[136:137], s[100:101]
	v_pk_add_f32 v[138:139], v[138:139], s[100:101]
	v_rcp_f32_e32 v132, v132
	v_rcp_f32_e32 v133, v133
	v_rcp_f32_e32 v134, v134
	v_rcp_f32_e32 v135, v135
	v_rcp_f32_e32 v136, v136
	v_rcp_f32_e32 v137, v137
	v_rcp_f32_e32 v138, v138
	v_rcp_f32_e32 v139, v139
	v_pk_mul_f32 v[12:13], v[12:13], v[132:133]
	v_pk_mul_f32 v[14:15], v[14:15], v[134:135]
	v_pk_mul_f32 v[4:5], v[4:5], v[136:137]
	v_pk_mul_f32 v[6:7], v[6:7], v[138:139]
	v_pk_mul_f32 v[12:13], v[12:13], v[8:9]
	v_pk_mul_f32 v[14:15], v[14:15], v[10:11]
	v_pk_mul_f32 v[4:5], v[4:5], v[0:1]
	v_pk_mul_f32 v[6:7], v[6:7], v[2:3]
	v_cvt_pk_bf16_f32 v186, v12, v13
	v_cvt_pk_bf16_f32 v187, v14, v15
	v_cvt_pk_bf16_f32 v188, v4, v5
	v_cvt_pk_bf16_f32 v189, v6, v7
	global_store_dwordx4 v[182:183], v[186:189], off offset:2048
	s_mov_b32 s101, 1
	s_mov_b64 s[0:1], -1
	s_andn2_b64 vcc, exec, s[4:5]
	s_cbranch_vccnz .LBB0_1127
	s_andn2_b64 vcc, exec, s[6:7]
	s_cbranch_vccnz .LBB0_1126
	s_barrier
	s_branch .LBB0_1126
